# phase-0 position-bias partial sums: 8 weight loads per unrolled step issued together (was one load, one full wait, one fmac at a time)
# baseline (speedup 1.0000x reference)
; __global__ void __launch_bounds__(256, 2) fwd_megakernel(Params p) {
;     ...
;         const int j = tid & 127, hh = tid >> 7;
;         float a = 0.f;
; #pragma unroll 8
;         for (int k = kc * 64 + hh * 32; k < kc * 64 + hh * 32 + 32; ++k) a += pos[k] * w1[(size_t)k * 128 + j];
.LBB0_32:
	global_load_dwordx4 v[52:55], v[36:37], off offset:-12
	global_load_dwordx4 v[56:59], v[36:37], off offset:-28
	global_load_dword v86, v[38:39], off
	global_load_dword v87, v[34:35], off
	global_load_dword v88, v[32:33], off
	global_load_dword v89, v[30:31], off
	v_mov_b32_e32 v103, 0
	v_add_u32_e32 v102, 4, v26
	v_lshlrev_b64 v[94:95], 9, v[102:103]
	v_lshl_add_u64 v[94:95], v[28:29], 0, v[94:95]
	global_load_dword v90, v[94:95], off
	v_add_u32_e32 v102, 5, v26
	v_lshlrev_b64 v[94:95], 9, v[102:103]
	v_lshl_add_u64 v[94:95], v[28:29], 0, v[94:95]
	global_load_dword v91, v[94:95], off
	v_add_u32_e32 v102, 6, v26
	v_lshlrev_b64 v[94:95], 9, v[102:103]
	v_lshl_add_u64 v[94:95], v[28:29], 0, v[94:95]
	global_load_dword v92, v[94:95], off
	v_add_u32_e32 v102, 7, v26
	v_lshlrev_b64 v[94:95], 9, v[102:103]
	v_lshl_add_u64 v[94:95], v[28:29], 0, v[94:95]
	global_load_dword v93, v[94:95], off
	v_lshl_add_u64 v[36:37], v[36:37], 0, 32
	v_lshl_add_u64 v[38:39], v[38:39], 0, s[20:21]
	v_lshl_add_u64 v[34:35], v[34:35], 0, s[20:21]
	v_lshl_add_u64 v[32:33], v[32:33], 0, s[20:21]
	v_lshl_add_u64 v[30:31], v[30:31], 0, s[20:21]
	v_add_u32_e32 v26, 8, v26
	v_cmp_ge_u32_e32 vcc, v26, v19
	s_or_b64 s[26:27], vcc, s[26:27]
	s_waitcnt vmcnt(0)
	v_fmac_f32_e32 v25, v56, v86
	v_fmac_f32_e32 v25, v57, v87
	v_fmac_f32_e32 v25, v58, v88
	v_fmac_f32_e32 v25, v59, v89
	v_fmac_f32_e32 v25, v52, v90
	v_fmac_f32_e32 v25, v53, v91
	v_fmac_f32_e32 v25, v54, v92
	v_fmac_f32_e32 v25, v55, v93
	s_andn2_b64 exec, exec, s[26:27]
	s_cbranch_execnz .LBB0_32
	s_or_b64 exec, exec, s[26:27]
